# sample_gemm32 x4 (P3a,P3b,P4,P7): all fragment loads issued together, counted waits; was 4-8 serialized load->wait->MFMA round trips
# speedup vs baseline: 1.0033x; 1.0033x over previous
; #define LAS __attribute__((address_space(3)))
; __device__ __forceinline__ void fold_item(const float* Win, const float* wgg, const float* kgain, bf16_t* WT, int k0, int j0, int n_dst0, LAS float* scr, int lane) {
;     float wg[GR];
; #pragma unroll
;     for (int r = 0; r < GR; ++r) wg[r] = wgg[r * GKW + j0 + (lane & 31)];
; #pragma unroll 8
;     for (int i = 0; i < 32; ++i) { const int kk = 2 * i + (lane >> 5); const f32x4* wr = (const f32x4*)(Win + (size_t)(k0 + kk) * NIN + C_GLR); float s = 0.f;
; #pragma unroll
;         for (int r4 = 0; r4 < GR / 4; ++r4) { const f32x4 x = wr[r4]; s += (x[0] * wg[4 * r4] + x[1] * wg[4 * r4 + 1]) + (x[2] * wg[4 * r4 + 2] + x[3] * wg[4 * r4 + 3]); }
;         scr[kk * 33 + (lane & 31)] = s * kgain[k0 + kk]; }
.LBB0_47:
	v_lshl_add_u64 v[54:55], v[52:53], 0, s[84:85]
	v_lshl_add_u64 v[86:87], v[54:55], 0, s[78:79]
	v_add_co_u32_e32 v54, vcc, 0x7000, v54
	s_nop 1
	v_addc_co_u32_e32 v55, vcc, 0, v55, vcc
	global_load_dwordx4 v[74:77], v[54:55], off
	global_load_dwordx4 v[78:81], v[86:87], off offset:32
	global_load_dwordx4 v[82:85], v[86:87], off offset:48
	s_nop 0
	global_load_dwordx4 v[86:89], v[86:87], off offset:16
	s_waitcnt vmcnt(3)
	v_mov_b32_e32 v54, v75
	v_mov_b32_e32 v75, v77
	v_mov_b32_e32 v55, v76
	v_pk_mul_f32 v[74:75], v[20:21], v[74:75]
	s_nop 0
	v_pk_fma_f32 v[54:55], v[22:23], v[54:55], v[74:75]
	s_waitcnt vmcnt(0)
	v_mov_b32_e32 v74, v87
	v_mov_b32_e32 v87, v89
	v_mov_b32_e32 v75, v88
	v_pk_mul_f32 v[76:77], v[24:25], v[86:87]
	v_add_f32_e32 v54, v54, v55
	v_pk_fma_f32 v[74:75], v[26:27], v[74:75], v[76:77]
	v_mul_f32_e32 v76, v70, v83
	v_pk_add_f32 v[74:75], v[74:75], v[74:75] op_sel:[0,1] op_sel_hi:[1,0]
	v_add_f32_e32 v54, 0, v54
	v_mul_f32_e32 v55, v12, v82
	v_mov_b32_e32 v75, v76
	v_pk_add_f32 v[54:55], v[54:55], v[74:75]
	v_mul_f32_e32 v74, v29, v79
	v_mul_f32_e32 v77, v71, v84
	v_pk_fma_f32 v[74:75], v[28:29], v[78:79], v[74:75] op_sel_hi:[1,1,0]
	v_mul_f32_e32 v76, v31, v81
	v_mul_f32_e32 v82, v72, v85
	v_mov_b32_e32 v75, v77
	v_pk_fma_f32 v[76:77], v[30:31], v[80:81], v[76:77] op_sel_hi:[1,1,0]
	s_nop 0
	v_mov_b32_e32 v77, v82
	v_pk_add_f32 v[74:75], v[74:75], v[76:77]
	s_nop 0
	v_pk_add_f32 v[54:55], v[54:55], v[74:75]
	s_nop 0
	v_add_f32_e32 v74, v54, v55
	v_lshl_add_u64 v[54:55], v[50:51], 0, v[46:47]
	global_load_dword v54, v[54:55], off
	v_lshl_add_u64 v[50:51], v[50:51], 0, 64
	s_waitcnt vmcnt(0)
	v_mul_f32_e32 v90, v54, v74
	v_lshl_add_u64 v[54:55], v[44:45], 0, s[84:85]
	v_lshl_add_u64 v[86:87], v[54:55], 0, s[78:79]
	v_add_co_u32_e32 v54, vcc, s25, v54
	s_nop 1
	v_addc_co_u32_e32 v55, vcc, 0, v55, vcc
	global_load_dwordx4 v[74:77], v[54:55], off
	global_load_dwordx4 v[78:81], v[86:87], off offset:32
	global_load_dwordx4 v[82:85], v[86:87], off offset:48
	s_nop 0
	global_load_dwordx4 v[86:89], v[86:87], off offset:16
	s_waitcnt vmcnt(3)
	v_mov_b32_e32 v54, v75
	v_mov_b32_e32 v75, v77
	v_mov_b32_e32 v55, v76
	v_pk_mul_f32 v[74:75], v[20:21], v[74:75]
	s_nop 0
	v_pk_fma_f32 v[54:55], v[22:23], v[54:55], v[74:75]
	s_waitcnt vmcnt(0)
	v_mov_b32_e32 v74, v87
	v_mov_b32_e32 v87, v89
	v_mov_b32_e32 v75, v88
	v_pk_mul_f32 v[76:77], v[24:25], v[86:87]
	v_add_f32_e32 v54, v54, v55
	v_pk_fma_f32 v[74:75], v[26:27], v[74:75], v[76:77]
	v_mul_f32_e32 v76, v70, v83
	v_pk_add_f32 v[74:75], v[74:75], v[74:75] op_sel:[0,1] op_sel_hi:[1,0]
	v_add_f32_e32 v54, 0, v54
	v_mul_f32_e32 v55, v12, v82
	v_mov_b32_e32 v75, v76
	v_pk_add_f32 v[54:55], v[54:55], v[74:75]
	v_mul_f32_e32 v74, v29, v79
	v_mul_f32_e32 v77, v71, v84
	v_pk_fma_f32 v[74:75], v[28:29], v[78:79], v[74:75] op_sel_hi:[1,1,0]
	v_mul_f32_e32 v76, v31, v81
	v_mul_f32_e32 v82, v72, v85
	v_mov_b32_e32 v75, v77
	v_pk_fma_f32 v[76:77], v[30:31], v[80:81], v[76:77] op_sel_hi:[1,1,0]
	s_nop 0
	v_mov_b32_e32 v77, v82
	v_pk_add_f32 v[74:75], v[74:75], v[76:77]
	s_nop 0
	v_pk_add_f32 v[54:55], v[54:55], v[74:75]
	s_nop 0
	v_add_f32_e32 v74, v54, v55
	v_lshl_add_u64 v[54:55], v[48:49], 0, v[46:47]
	global_load_dword v75, v[54:55], off offset:8
	v_lshl_add_u64 v[48:49], v[48:49], 0, 64
	s_waitcnt vmcnt(0)
	v_mul_f32_e32 v74, v75, v74
	ds_write2_b32 v73, v90, v74 offset1:66
	v_lshl_add_u64 v[74:75], v[42:43], 0, s[84:85]
	v_lshl_add_u64 v[86:87], v[74:75], 0, s[78:79]
	v_add_co_u32_e32 v74, vcc, s25, v74
	s_nop 1
	v_addc_co_u32_e32 v75, vcc, 0, v75, vcc
	global_load_dwordx4 v[74:77], v[74:75], off
	s_nop 0
	global_load_dwordx4 v[78:81], v[86:87], off offset:32
	global_load_dwordx4 v[82:85], v[86:87], off offset:48
	s_nop 0
	global_load_dwordx4 v[86:89], v[86:87], off offset:16
	s_waitcnt vmcnt(3)
	v_mov_b32_e32 v90, v75
	v_mov_b32_e32 v91, v76
	v_mov_b32_e32 v75, v77
	s_waitcnt vmcnt(0)
	v_mov_b32_e32 v76, v87
	v_mov_b32_e32 v87, v89
	v_pk_mul_f32 v[74:75], v[20:21], v[74:75]
	v_mov_b32_e32 v77, v88
	v_pk_mul_f32 v[86:87], v[24:25], v[86:87]
	v_pk_fma_f32 v[74:75], v[22:23], v[90:91], v[74:75]
	v_pk_fma_f32 v[76:77], v[26:27], v[76:77], v[86:87]
	v_add_f32_e32 v74, v74, v75
	v_mul_f32_e32 v75, v12, v82
	v_mul_f32_e32 v82, v70, v83
	v_pk_add_f32 v[76:77], v[76:77], v[76:77] op_sel:[0,1] op_sel_hi:[1,0]
	v_add_f32_e32 v74, 0, v74
	v_mov_b32_e32 v77, v82
	v_pk_add_f32 v[74:75], v[74:75], v[76:77]
	v_mul_f32_e32 v76, v29, v79
	v_pk_fma_f32 v[76:77], v[28:29], v[78:79], v[76:77] op_sel_hi:[1,1,0]
	v_mul_f32_e32 v78, v31, v81
	v_mul_f32_e32 v83, v71, v84
	v_mul_f32_e32 v84, v72, v85
	v_pk_fma_f32 v[78:79], v[30:31], v[80:81], v[78:79] op_sel_hi:[1,1,0]
	v_mov_b32_e32 v77, v83
	v_mov_b32_e32 v79, v84
	v_pk_add_f32 v[76:77], v[76:77], v[78:79]
	s_nop 0
	v_pk_add_f32 v[74:75], v[74:75], v[76:77]
	s_nop 0
	v_add_f32_e32 v74, v74, v75
	global_load_dword v75, v[54:55], off offset:16
	s_waitcnt vmcnt(0)
	v_mul_f32_e32 v92, v75, v74
	v_lshl_add_u64 v[74:75], v[40:41], 0, s[84:85]
	v_lshl_add_u64 v[86:87], v[74:75], 0, s[78:79]
	v_add_co_u32_e32 v74, vcc, s25, v74
	s_nop 1
	v_addc_co_u32_e32 v75, vcc, 0, v75, vcc
	global_load_dwordx4 v[74:77], v[74:75], off
	s_nop 0
	global_load_dwordx4 v[78:81], v[86:87], off offset:32
	global_load_dwordx4 v[82:85], v[86:87], off offset:48
	s_nop 0
	global_load_dwordx4 v[86:89], v[86:87], off offset:16
	s_waitcnt vmcnt(3)
	v_mov_b32_e32 v90, v75
	v_mov_b32_e32 v91, v76
	v_mov_b32_e32 v75, v77
	s_waitcnt vmcnt(0)
; __device__ __forceinline__ void fold_item(const float* Win, const float* wgg, const float* kgain, bf16_t* WT, int k0, int j0, int n_dst0, LAS float* scr, int lane) {
;     ...
;     for (int i = 0; i < 32; ++i) { const int kk = 2 * i + (lane >> 5); const f32x4* wr = (const f32x4*)(Win + (size_t)(k0 + kk) * NIN + C_GLR); float s = 0.f;
; #pragma unroll
;         for (int r4 = 0; r4 < GR / 4; ++r4) { const f32x4 x = wr[r4]; s += (x[0] * wg[4 * r4] + x[1] * wg[4 * r4 + 1]) + (x[2] * wg[4 * r4 + 2] + x[3] * wg[4 * r4 + 3]); }
;         scr[kk * 33 + (lane & 31)] = s * kgain[k0 + kk]; }
	v_mov_b32_e32 v76, v87
	v_mov_b32_e32 v87, v89
	v_pk_mul_f32 v[74:75], v[20:21], v[74:75]
	v_mov_b32_e32 v77, v88
	v_pk_mul_f32 v[86:87], v[24:25], v[86:87]
	v_pk_fma_f32 v[74:75], v[22:23], v[90:91], v[74:75]
	v_pk_fma_f32 v[76:77], v[26:27], v[76:77], v[86:87]
	v_add_f32_e32 v74, v74, v75
	v_mul_f32_e32 v75, v12, v82
	v_mul_f32_e32 v82, v70, v83
	v_pk_add_f32 v[76:77], v[76:77], v[76:77] op_sel:[0,1] op_sel_hi:[1,0]
	v_add_f32_e32 v74, 0, v74
	v_mov_b32_e32 v77, v82
	v_pk_add_f32 v[74:75], v[74:75], v[76:77]
	v_mul_f32_e32 v76, v29, v79
	v_pk_fma_f32 v[76:77], v[28:29], v[78:79], v[76:77] op_sel_hi:[1,1,0]
	v_mul_f32_e32 v78, v31, v81
	v_mul_f32_e32 v83, v71, v84
	v_mul_f32_e32 v84, v72, v85
	v_pk_fma_f32 v[78:79], v[30:31], v[80:81], v[78:79] op_sel_hi:[1,1,0]
	v_mov_b32_e32 v77, v83
	v_mov_b32_e32 v79, v84
	v_pk_add_f32 v[76:77], v[76:77], v[78:79]
	s_nop 0
	v_pk_add_f32 v[74:75], v[74:75], v[76:77]
	s_nop 0
	v_add_f32_e32 v74, v74, v75
	global_load_dword v75, v[54:55], off offset:24
	s_waitcnt vmcnt(0)
	v_mul_f32_e32 v74, v75, v74
	ds_write2_b32 v73, v92, v74 offset0:132 offset1:198
	v_lshl_add_u64 v[74:75], v[38:39], 0, s[84:85]
	v_lshl_add_u64 v[86:87], v[74:75], 0, s[78:79]
	v_add_co_u32_e32 v74, vcc, s25, v74
	s_nop 1
	v_addc_co_u32_e32 v75, vcc, 0, v75, vcc
	global_load_dwordx4 v[74:77], v[74:75], off
	s_nop 0
	global_load_dwordx4 v[78:81], v[86:87], off offset:32
	global_load_dwordx4 v[82:85], v[86:87], off offset:48
	s_nop 0
	global_load_dwordx4 v[86:89], v[86:87], off offset:16
	s_waitcnt vmcnt(3)
	v_mov_b32_e32 v90, v75
	v_mov_b32_e32 v91, v76
	v_mov_b32_e32 v75, v77
	s_waitcnt vmcnt(0)
	v_mov_b32_e32 v76, v87
	v_mov_b32_e32 v87, v89
	v_pk_mul_f32 v[74:75], v[20:21], v[74:75]
	v_mov_b32_e32 v77, v88
	v_pk_mul_f32 v[86:87], v[24:25], v[86:87]
	v_pk_fma_f32 v[74:75], v[22:23], v[90:91], v[74:75]
	v_pk_fma_f32 v[76:77], v[26:27], v[76:77], v[86:87]
	v_add_f32_e32 v74, v74, v75
	v_mul_f32_e32 v75, v12, v82
	v_mul_f32_e32 v82, v70, v83
	v_pk_add_f32 v[76:77], v[76:77], v[76:77] op_sel:[0,1] op_sel_hi:[1,0]
	v_add_f32_e32 v74, 0, v74
	v_mov_b32_e32 v77, v82
	v_pk_add_f32 v[74:75], v[74:75], v[76:77]
	v_mul_f32_e32 v76, v29, v79
	v_pk_fma_f32 v[76:77], v[28:29], v[78:79], v[76:77] op_sel_hi:[1,1,0]
	v_mul_f32_e32 v78, v31, v81
	v_mul_f32_e32 v83, v71, v84
	v_mul_f32_e32 v84, v72, v85
	v_pk_fma_f32 v[78:79], v[30:31], v[80:81], v[78:79] op_sel_hi:[1,1,0]
	v_mov_b32_e32 v77, v83
	v_mov_b32_e32 v79, v84
	v_pk_add_f32 v[76:77], v[76:77], v[78:79]
	s_nop 0
	v_pk_add_f32 v[74:75], v[74:75], v[76:77]
	s_nop 0
	v_add_f32_e32 v74, v74, v75
	global_load_dword v75, v[54:55], off offset:32
	s_waitcnt vmcnt(0)
	v_mul_f32_e32 v92, v75, v74
	v_lshl_add_u64 v[74:75], v[36:37], 0, s[84:85]
	v_lshl_add_u64 v[86:87], v[74:75], 0, s[78:79]
	v_add_co_u32_e32 v74, vcc, s25, v74
	s_nop 1
	v_addc_co_u32_e32 v75, vcc, 0, v75, vcc
	global_load_dwordx4 v[74:77], v[74:75], off
	s_nop 0
	global_load_dwordx4 v[78:81], v[86:87], off offset:32
	global_load_dwordx4 v[82:85], v[86:87], off offset:48
	s_nop 0
	global_load_dwordx4 v[86:89], v[86:87], off offset:16
	s_waitcnt vmcnt(3)
	v_mov_b32_e32 v90, v75
	v_mov_b32_e32 v91, v76
	v_mov_b32_e32 v75, v77
	s_waitcnt vmcnt(0)
	v_mov_b32_e32 v76, v87
	v_mov_b32_e32 v87, v89
	v_pk_mul_f32 v[74:75], v[20:21], v[74:75]
	v_mov_b32_e32 v77, v88
	v_pk_mul_f32 v[86:87], v[24:25], v[86:87]
	v_pk_fma_f32 v[74:75], v[22:23], v[90:91], v[74:75]
	v_pk_fma_f32 v[76:77], v[26:27], v[76:77], v[86:87]
	v_add_f32_e32 v74, v74, v75
	v_mul_f32_e32 v75, v12, v82
	v_mul_f32_e32 v82, v70, v83
	v_pk_add_f32 v[76:77], v[76:77], v[76:77] op_sel:[0,1] op_sel_hi:[1,0]
	v_add_f32_e32 v74, 0, v74
	v_mov_b32_e32 v77, v82
	v_pk_add_f32 v[74:75], v[74:75], v[76:77]
	v_mul_f32_e32 v76, v29, v79
	v_pk_fma_f32 v[76:77], v[28:29], v[78:79], v[76:77] op_sel_hi:[1,1,0]
	v_mul_f32_e32 v78, v31, v81
	v_mul_f32_e32 v83, v71, v84
	v_mul_f32_e32 v84, v72, v85
	v_pk_fma_f32 v[78:79], v[30:31], v[80:81], v[78:79] op_sel_hi:[1,1,0]
	v_mov_b32_e32 v77, v83
	v_mov_b32_e32 v79, v84
	v_pk_add_f32 v[76:77], v[76:77], v[78:79]
	s_nop 0
	v_pk_add_f32 v[74:75], v[74:75], v[76:77]
	v_lshl_add_u64 v[76:77], v[34:35], 0, s[84:85]
	v_add_f32_e32 v74, v74, v75
	global_load_dword v75, v[54:55], off offset:40
	v_lshl_add_u64 v[88:89], v[76:77], 0, s[78:79]
	v_add_co_u32_e32 v76, vcc, s25, v76
	s_waitcnt vmcnt(0)
	v_mul_f32_e32 v75, v75, v74
	v_add_u32_e32 v74, 0x400, v73
	ds_write2_b32 v74, v92, v75 offset0:8 offset1:74
	v_addc_co_u32_e32 v77, vcc, 0, v77, vcc
	global_load_dwordx4 v[76:79], v[76:77], off
	s_nop 0
	global_load_dwordx4 v[80:83], v[88:89], off offset:32
	global_load_dwordx4 v[84:87], v[88:89], off offset:48
	s_nop 0
	global_load_dwordx4 v[88:91], v[88:89], off offset:16
	v_add_u32_e32 v73, 0x840, v73
	s_waitcnt vmcnt(3)
	v_mov_b32_e32 v92, v77
	v_mov_b32_e32 v77, v79
	v_mov_b32_e32 v93, v78
	v_pk_mul_f32 v[76:77], v[20:21], v[76:77]
	s_waitcnt vmcnt(0)
; #define LAS __attribute__((address_space(3)))
; __device__ __forceinline__ unsigned pk2(float lo, float hi) { return pg8::cvt_pk_bf16(lo, hi); }
; __device__ __forceinline__ void fold_item(const float* Win, const float* wgg, const float* kgain, bf16_t* WT, int k0, int j0, int n_dst0, LAS float* scr, int lane) {
;     ...
;     for (int i = 0; i < 32; ++i) { const int kk = 2 * i + (lane >> 5); const f32x4* wr = (const f32x4*)(Win + (size_t)(k0 + kk) * NIN + C_GLR); float s = 0.f;
; #pragma unroll
;         for (int r4 = 0; r4 < GR / 4; ++r4) { const f32x4 x = wr[r4]; s += (x[0] * wg[4 * r4] + x[1] * wg[4 * r4 + 1]) + (x[2] * wg[4 * r4 + 2] + x[3] * wg[4 * r4 + 3]); }
;         scr[kk * 33 + (lane & 31)] = s * kgain[k0 + kk]; }
;     asm volatile("s_waitcnt lgkmcnt(0)" ::: "memory");
;     const int c = lane & 7;
; #pragma unroll
;     for (int j = 0; j < 4; ++j) { const int n = (lane >> 3) + 8 * j; const LAS float* s = scr + (8 * c) * 33 + n;
;         u32x4 o; o.x = pk2(s[0 * 33], s[1 * 33]); o.y = pk2(s[2 * 33], s[3 * 33]); o.z = pk2(s[4 * 33], s[5 * 33]); o.w = pk2(s[6 * 33], s[7 * 33]);
;         *(u32x4*)(WT + (size_t)(n_dst0 + n) * D + k0 + 8 * c) = o; }
;     asm volatile("s_waitcnt lgkmcnt(0)" ::: "memory");
	v_mov_b32_e32 v78, v89
	v_mov_b32_e32 v89, v91
	v_pk_fma_f32 v[76:77], v[22:23], v[92:93], v[76:77]
	v_mov_b32_e32 v79, v90
	v_pk_mul_f32 v[88:89], v[24:25], v[88:89]
	v_add_f32_e32 v75, v76, v77
	v_pk_fma_f32 v[78:79], v[26:27], v[78:79], v[88:89]
	v_add_f32_e32 v76, 0, v75
	v_mul_f32_e32 v75, v70, v85
	v_pk_add_f32 v[78:79], v[78:79], v[78:79] op_sel:[0,1] op_sel_hi:[1,0]
	v_mul_f32_e32 v77, v12, v84
	v_mov_b32_e32 v79, v75
	v_pk_add_f32 v[76:77], v[76:77], v[78:79]
	v_mul_f32_e32 v78, v29, v81
	v_pk_fma_f32 v[78:79], v[28:29], v[80:81], v[78:79] op_sel_hi:[1,1,0]
	v_mul_f32_e32 v80, v31, v83
	v_mul_f32_e32 v84, v71, v86
	v_mul_f32_e32 v85, v72, v87
	v_pk_fma_f32 v[80:81], v[30:31], v[82:83], v[80:81] op_sel_hi:[1,1,0]
	v_mov_b32_e32 v79, v84
	v_mov_b32_e32 v81, v85
	v_pk_add_f32 v[78:79], v[78:79], v[80:81]
	s_nop 0
	v_pk_add_f32 v[76:77], v[76:77], v[78:79]
	s_nop 0
	v_add_f32_e32 v75, v76, v77
	global_load_dword v76, v[54:55], off offset:48
	s_waitcnt vmcnt(0)
	v_mul_f32_e32 v75, v76, v75
	v_lshl_add_u64 v[76:77], v[32:33], 0, s[84:85]
	v_lshl_add_u64 v[88:89], v[76:77], 0, s[78:79]
	v_add_co_u32_e32 v76, vcc, s25, v76
	s_add_u32 s84, s84, 0xb0400
	s_nop 0
	v_addc_co_u32_e32 v77, vcc, 0, v77, vcc
	global_load_dwordx4 v[76:79], v[76:77], off
	s_nop 0
	global_load_dwordx4 v[80:83], v[88:89], off offset:32
	global_load_dwordx4 v[84:87], v[88:89], off offset:48
	s_nop 0
	global_load_dwordx4 v[88:91], v[88:89], off offset:16
	s_addc_u32 s85, s85, 0
	global_load_dword v54, v[54:55], off offset:56
	s_cmp_lg_u32 s84, 0x2c1000
	s_waitcnt vmcnt(4)
	v_mov_b32_e32 v92, v77
	v_mov_b32_e32 v93, v78
	v_mov_b32_e32 v77, v79
	s_waitcnt vmcnt(1)
	v_mov_b32_e32 v78, v89
	v_mov_b32_e32 v89, v91
	v_pk_mul_f32 v[76:77], v[20:21], v[76:77]
	v_mov_b32_e32 v79, v90
	v_pk_mul_f32 v[88:89], v[24:25], v[88:89]
	v_pk_fma_f32 v[76:77], v[22:23], v[92:93], v[76:77]
	v_pk_fma_f32 v[78:79], v[26:27], v[78:79], v[88:89]
	v_add_f32_e32 v76, v76, v77
	v_mul_f32_e32 v77, v12, v84
	v_mul_f32_e32 v84, v70, v85
	v_pk_add_f32 v[78:79], v[78:79], v[78:79] op_sel:[0,1] op_sel_hi:[1,0]
	v_add_f32_e32 v76, 0, v76
	v_mov_b32_e32 v79, v84
	v_pk_add_f32 v[76:77], v[76:77], v[78:79]
	v_mul_f32_e32 v78, v29, v81
	v_pk_fma_f32 v[78:79], v[28:29], v[80:81], v[78:79] op_sel_hi:[1,1,0]
	v_mul_f32_e32 v80, v31, v83
	v_mul_f32_e32 v85, v71, v86
	v_mul_f32_e32 v86, v72, v87
	v_pk_fma_f32 v[80:81], v[30:31], v[82:83], v[80:81] op_sel_hi:[1,1,0]
	v_mov_b32_e32 v79, v85
	v_mov_b32_e32 v81, v86
	v_pk_add_f32 v[78:79], v[78:79], v[80:81]
	s_nop 0
	v_pk_add_f32 v[76:77], v[76:77], v[78:79]
	s_nop 0
	v_add_f32_e32 v76, v76, v77
	s_waitcnt vmcnt(0)
	v_mul_f32_e32 v54, v54, v76
	ds_write2_b32 v74, v75, v54 offset0:140 offset1:206
	s_cbranch_scc1 .LBB0_47
	s_waitcnt lgkmcnt(0)
	ds_read2_b32 v[20:21], v11 offset0:33 offset1:41
	ds_read2_b32 v[22:23], v11 offset1:8
	ds_read2_b32 v[24:25], v11 offset0:66 offset1:74
	ds_read2_b32 v[26:27], v11 offset0:99 offset1:107
	ds_read2_b32 v[28:29], v11 offset0:132 offset1:140
	ds_read2_b32 v[30:31], v11 offset0:165 offset1:173
	ds_read2_b32 v[32:33], v11 offset0:198 offset1:206
	ds_read2_b32 v[34:35], v11 offset0:231 offset1:239
	v_lshl_add_u64 v[16:17], v[18:19], 1, v[16:17]
	v_lshlrev_b32_e32 v12, 1, v14
	v_lshl_add_u64 v[36:37], v[16:17], 0, v[12:13]
	v_or_b32_e32 v12, v69, v7
	v_lshlrev_b32_e32 v12, 12, v12
	s_waitcnt lgkmcnt(6)
	v_cvt_pk_bf16_f32 v16, v22, v20
	s_waitcnt lgkmcnt(4)
	v_cvt_pk_bf16_f32 v17, v24, v26
	s_waitcnt lgkmcnt(2)
	v_cvt_pk_bf16_f32 v18, v28, v30
	s_waitcnt lgkmcnt(0)
	v_cvt_pk_bf16_f32 v19, v32, v34
	v_lshl_add_u64 v[38:39], v[36:37], 0, v[12:13]
	global_store_dwordx4 v[38:39], v[16:19], off
	v_or_b32_e32 v12, v69, v15
	v_lshlrev_b32_e32 v12, 12, v12
	v_cvt_pk_bf16_f32 v16, v23, v21
	v_cvt_pk_bf16_f32 v17, v25, v27
	v_cvt_pk_bf16_f32 v18, v29, v31
	v_cvt_pk_bf16_f32 v19, v33, v35
	ds_read2_b32 v[22:23], v11 offset0:49 offset1:57
	ds_read2_b32 v[24:25], v11 offset0:16 offset1:24
	ds_read2_b32 v[26:27], v11 offset0:82 offset1:90
	ds_read2_b32 v[28:29], v11 offset0:115 offset1:123
	ds_read2_b32 v[30:31], v11 offset0:148 offset1:156
	ds_read2_b32 v[32:33], v11 offset0:181 offset1:189
	ds_read2_b32 v[34:35], v11 offset0:214 offset1:222
	ds_read2_b32 v[38:39], v11 offset0:247 offset1:255
	v_lshl_add_u64 v[20:21], v[36:37], 0, v[12:13]
	v_or_b32_e32 v12, v69, v56
	v_lshlrev_b32_e32 v12, 12, v12
	global_store_dwordx4 v[20:21], v[16:19], off
	v_lshl_add_u64 v[20:21], v[36:37], 0, v[12:13]
	v_or_b32_e32 v12, v69, v57
	s_waitcnt lgkmcnt(6)
	v_cvt_pk_bf16_f32 v16, v24, v22
	s_waitcnt lgkmcnt(4)
	v_cvt_pk_bf16_f32 v17, v26, v28
	s_waitcnt lgkmcnt(2)
	v_cvt_pk_bf16_f32 v18, v30, v32
	s_waitcnt lgkmcnt(0)
	v_cvt_pk_bf16_f32 v19, v34, v38
	v_lshlrev_b32_e32 v12, 12, v12
	global_store_dwordx4 v[20:21], v[16:19], off
	v_lshl_add_u64 v[20:21], v[36:37], 0, v[12:13]
	s_nop 0
	v_cvt_pk_bf16_f32 v16, v25, v23
	v_cvt_pk_bf16_f32 v17, v27, v29
	v_cvt_pk_bf16_f32 v18, v31, v33
	v_cvt_pk_bf16_f32 v19, v35, v39
	global_store_dwordx4 v[20:21], v[16:19], off
	s_waitcnt lgkmcnt(0)
	s_branch .LBB0_10

; template <int MODE, int NST, class F>
; __device__ __forceinline__ void sample_gemm32(const bf16_t* A, int lda, const bf16_t* Bt, int ldb, int N, const F& f, float* aux, LAS unsigned char* lds, int wg, int nwg) {
;     ...
;     for (int item = wg; item < nitems; item += nwg) {
;         const int rb = item & 3, cb = item >> 2;
;         const char* abase = (const char*)(A + (size_t)(rb * 32) * lda + w * Kw);
;         const char* bbase = (const char*)(Bt + (size_t)(cb * 32) * ldb + w * Kw);
;         unsigned aoff[2], boff[2];
; #pragma unroll
;         for (int t2 = 0; t2 < 2; ++t2) { aoff[t2] = (unsigned)((t2 * 16 + fr) * lda + fq * 8) * 2u; boff[t2] = (unsigned)((t2 * 16 + fr) * ldb + fq * 8) * 2u; }
;         bf16x8_t av[NST][2], bv[NST][2];
; #pragma unroll
;         for (int st = 0; st < NST; ++st)
; #pragma unroll
;             for (int t2 = 0; t2 < 2; ++t2) { av[st][t2] = *(const bf16x8_t*)(abase + st * 64 + aoff[t2]); bv[st][t2] = *(const bf16x8_t*)(bbase + st * 64 + boff[t2]); }
;         f32x4 acc[2][2];
; #pragma unroll
;         for (int mt = 0; mt < 2; ++mt)
; #pragma unroll
;             for (int nt = 0; nt < 2; ++nt) acc[mt][nt] = (f32x4){0.f, 0.f, 0.f, 0.f};
; #pragma unroll
;         for (int st = 0; st < NST; ++st)
; #pragma unroll
;             for (int mt = 0; mt < 2; ++mt)
; #pragma unroll
;                 for (int nt = 0; nt < 2; ++nt) acc[mt][nt] = MFMA16(bv[st][nt], av[st][mt], acc[mt][nt]);
;         __syncthreads();
;         LAS float* tk = tile + w * (32 * SG32_LD);
; #pragma unroll
;         for (int mt = 0; mt < 2; ++mt)
; #pragma unroll
;             for (int nt = 0; nt < 2; ++nt) *(LAS f32x4*)(tk + (mt * 16 + fr) * SG32_LD + nt * 16 + fq * 4) = acc[mt][nt];
;         __syncthreads();
;         if (tid < 128) {
;             const int r = tid >> 2, cq = (tid & 3) * 8;
;             f32x4 x0 = *(const LAS f32x4*)(tile + r * SG32_LD + cq), x1 = *(const LAS f32x4*)(tile + r * SG32_LD + cq + 4);
; #pragma unroll
;             for (int q = 1; q < 8; ++q) { x0 += *(const LAS f32x4*)(tile + q * (32 * SG32_LD) + r * SG32_LD + cq); x1 += *(const LAS f32x4*)(tile + q * (32 * SG32_LD) + r * SG32_LD + cq + 4); }
;             const float v[8] = {x0[0], x0[1], x0[2], x0[3], x1[0], x1[1], x1[2], x1[3]};
;             const int row = MP + rb * 32 + r;
;             if constexpr (MODE == 0) f.apply8(row, cb * 32 + cq, v, f.rowctx(row));
.LBB0_1223:
	s_and_b32 s20, s24, 0xffffffe0
	s_and_b32 s29, s26, 0x60
	s_ashr_i32 s21, s20, 31
	s_lshl_b64 s[18:19], s[20:21], 11
	s_lshl_b32 s21, s29, 12
	s_add_u32 s30, s6, s21
	s_addc_u32 s31, s7, 0
	s_add_u32 s18, s22, s18
	s_addc_u32 s19, s23, s19
	v_lshl_add_u64 v[12:13], s[18:19], 0, v[6:7]
	v_lshl_add_u64 v[42:43], s[30:31], 0, v[172:173]
	v_lshl_add_u64 v[44:45], s[18:19], 0, v[10:11]
	v_lshl_add_u64 v[46:47], s[30:31], 0, v[8:9]
	global_load_dwordx4 v[48:51], v[12:13], off
	global_load_dwordx4 v[52:55], v[42:43], off
	global_load_dwordx4 v[56:59], v[44:45], off
	global_load_dwordx4 v[60:63], v[46:47], off
	global_load_dwordx4 v[64:67], v[12:13], off offset:64
	global_load_dwordx4 v[68:71], v[42:43], off offset:64
	global_load_dwordx4 v[72:75], v[44:45], off offset:64
	global_load_dwordx4 v[76:79], v[46:47], off offset:64
	global_load_dwordx4 v[80:83], v[12:13], off offset:128
	global_load_dwordx4 v[84:87], v[42:43], off offset:128
	global_load_dwordx4 v[88:91], v[44:45], off offset:128
	global_load_dwordx4 v[92:95], v[46:47], off offset:128
	global_load_dwordx4 v[96:99], v[12:13], off offset:192
	global_load_dwordx4 v[100:103], v[42:43], off offset:192
	global_load_dwordx4 v[104:107], v[44:45], off offset:192
	global_load_dwordx4 v[108:111], v[46:47], off offset:192
	s_waitcnt vmcnt(12)
	v_mfma_f32_16x16x32_bf16 v[22:25], v[48:51], v[52:55], 0
	v_mfma_f32_16x16x32_bf16 v[18:21], v[56:59], v[52:55], 0
	v_mfma_f32_16x16x32_bf16 v[2:5], v[48:51], v[60:63], 0
	v_mfma_f32_16x16x32_bf16 v[26:29], v[56:59], v[60:63], 0
	s_waitcnt vmcnt(8)
	v_mfma_f32_16x16x32_bf16 v[22:25], v[64:67], v[68:71], v[22:25]
	v_mfma_f32_16x16x32_bf16 v[18:21], v[72:75], v[68:71], v[18:21]
	v_mfma_f32_16x16x32_bf16 v[2:5], v[64:67], v[76:79], v[2:5]
	v_mfma_f32_16x16x32_bf16 v[26:29], v[72:75], v[76:79], v[26:29]
	s_waitcnt vmcnt(4)
	v_mfma_f32_16x16x32_bf16 v[22:25], v[80:83], v[84:87], v[22:25]
	v_mfma_f32_16x16x32_bf16 v[18:21], v[88:91], v[84:87], v[18:21]
	v_mfma_f32_16x16x32_bf16 v[2:5], v[80:83], v[92:95], v[2:5]
	v_mfma_f32_16x16x32_bf16 v[26:29], v[88:91], v[92:95], v[26:29]
	s_waitcnt vmcnt(0)
	v_mfma_f32_16x16x32_bf16 v[22:25], v[96:99], v[100:103], v[22:25]
	v_mfma_f32_16x16x32_bf16 v[18:21], v[104:107], v[100:103], v[18:21]
	v_mfma_f32_16x16x32_bf16 v[2:5], v[96:99], v[108:111], v[2:5]
	v_mfma_f32_16x16x32_bf16 v[26:29], v[104:107], v[108:111], v[26:29]
	s_barrier
	s_nop 7
	s_nop 1
	ds_write_b128 v17, v[22:25]
	ds_write_b128 v17, v[18:21] offset:64
	ds_write_b128 v17, v[2:5] offset:2304
	ds_write_b128 v17, v[26:29] offset:2368
	s_waitcnt lgkmcnt(0)
	s_barrier
	s_and_saveexec_b64 s[18:19], vcc
	s_cbranch_execz .LBB0_1222
	ds_read_b128 v[2:5], v15
	ds_read_b128 v[18:21], v15 offset:16
	ds_read_b128 v[22:25], v15 offset:4608
	s_waitcnt lgkmcnt(0)
	v_pk_add_f32 v[12:13], v[4:5], v[24:25]
	v_pk_add_f32 v[22:23], v[2:3], v[22:23]
	ds_read_b128 v[2:5], v15 offset:4624
	s_waitcnt lgkmcnt(0)
	v_pk_add_f32 v[20:21], v[20:21], v[4:5]
	v_pk_add_f32 v[18:19], v[18:19], v[2:3]
	ds_read_b128 v[2:5], v15 offset:9216
	s_waitcnt lgkmcnt(0)
	v_pk_add_f32 v[12:13], v[12:13], v[4:5]
	v_pk_add_f32 v[22:23], v[22:23], v[2:3]
	ds_read_b128 v[2:5], v15 offset:9232
	s_waitcnt lgkmcnt(0)
	v_pk_add_f32 v[20:21], v[20:21], v[4:5]
	v_pk_add_f32 v[18:19], v[18:19], v[2:3]
	ds_read_b128 v[2:5], v15 offset:13824
	s_waitcnt lgkmcnt(0)
	v_pk_add_f32 v[12:13], v[12:13], v[4:5]
	v_pk_add_f32 v[22:23], v[22:23], v[2:3]
	ds_read_b128 v[2:5], v15 offset:13840
	s_waitcnt lgkmcnt(0)
	v_pk_add_f32 v[20:21], v[20:21], v[4:5]
	v_pk_add_f32 v[18:19], v[18:19], v[2:3]
	ds_read_b128 v[2:5], v15 offset:18432
	s_waitcnt lgkmcnt(0)
	v_pk_add_f32 v[12:13], v[12:13], v[4:5]
	v_pk_add_f32 v[22:23], v[22:23], v[2:3]
	ds_read_b128 v[2:5], v15 offset:18448
	s_waitcnt lgkmcnt(0)
	v_pk_add_f32 v[20:21], v[20:21], v[4:5]
	v_pk_add_f32 v[18:19], v[18:19], v[2:3]
	ds_read_b128 v[2:5], v15 offset:23040
	s_waitcnt lgkmcnt(0)
	v_pk_add_f32 v[12:13], v[12:13], v[4:5]
	v_pk_add_f32 v[22:23], v[22:23], v[2:3]
	ds_read_b128 v[2:5], v15 offset:23056
	s_waitcnt lgkmcnt(0)
	v_pk_add_f32 v[20:21], v[20:21], v[4:5]
	v_pk_add_f32 v[18:19], v[18:19], v[2:3]
	ds_read_b128 v[2:5], v15 offset:27648
	s_waitcnt lgkmcnt(0)
	v_pk_add_f32 v[12:13], v[12:13], v[4:5]
	v_pk_add_f32 v[22:23], v[22:23], v[2:3]
	ds_read_b128 v[2:5], v15 offset:27664
	s_waitcnt lgkmcnt(0)
	v_pk_add_f32 v[20:21], v[20:21], v[4:5]
	v_pk_add_f32 v[18:19], v[18:19], v[2:3]
	ds_read_b128 v[2:5], v15 offset:32256
	s_waitcnt lgkmcnt(0)
	v_pk_add_f32 v[24:25], v[12:13], v[4:5]
	v_pk_add_f32 v[22:23], v[22:23], v[2:3]
	ds_read_b128 v[2:5], v15 offset:32272
	s_waitcnt lgkmcnt(0)
	v_pk_add_f32 v[18:19], v[18:19], v[2:3]
	v_add_u32_e32 v2, s29, v16
	v_pk_add_f32 v[20:21], v[20:21], v[4:5]
	v_or_b32_e32 v4, s20, v14
	v_ashrrev_i32_e32 v3, 31, v2
	v_lshlrev_b64 v[26:27], 12, v[2:3]
	v_ashrrev_i32_e32 v5, 31, v4
	v_lshl_add_u64 v[2:3], s[14:15], 0, v[26:27]
	v_lshlrev_b64 v[12:13], 1, v[4:5]
	v_lshl_add_u64 v[2:3], v[2:3], 0, v[12:13]
	global_load_dwordx4 v[2:5], v[2:3], off
	s_waitcnt vmcnt(0)
	v_lshlrev_b32_e32 v28, 16, v2
	v_and_b32_e32 v29, 0xffff0000, v2
	v_lshlrev_b32_e32 v2, 16, v3
	v_and_b32_e32 v3, 0xffff0000, v3
	v_pk_mul_f32 v[24:25], v[24:25], v[2:3]
	v_lshlrev_b32_e32 v2, 16, v4
	v_and_b32_e32 v3, 0xffff0000, v4
	v_pk_mul_f32 v[18:19], v[18:19], v[2:3]
	v_lshlrev_b32_e32 v2, 16, v5
	v_and_b32_e32 v3, 0xffff0000, v5
	v_pk_mul_f32 v[22:23], v[22:23], v[28:29]
	v_pk_mul_f32 v[20:21], v[20:21], v[2:3]
	v_cvt_pk_bf16_f32 v4, v18, v19
	v_lshl_add_u64 v[18:19], s[8:9], 0, v[26:27]
	v_cvt_pk_bf16_f32 v2, v22, v23
	v_cvt_pk_bf16_f32 v3, v24, v25
	v_cvt_pk_bf16_f32 v5, v20, v21
	v_lshl_add_u64 v[12:13], v[18:19], 0, v[12:13]
	global_store_dwordx4 v[12:13], v[2:5], off
	s_branch .LBB0_1222

; template <int MODE, int NST, class F>
; __device__ __forceinline__ void sample_gemm32(const bf16_t* A, int lda, const bf16_t* Bt, int ldb, int N, const F& f, float* aux, LAS unsigned char* lds, int wg, int nwg) {
;     ...
;     for (int item = wg; item < nitems; item += nwg) {
;         const int rb = item & 3, cb = item >> 2;
;         const char* abase = (const char*)(A + (size_t)(rb * 32) * lda + w * Kw);
;         const char* bbase = (const char*)(Bt + (size_t)(cb * 32) * ldb + w * Kw);
;         unsigned aoff[2], boff[2];
; #pragma unroll
;         for (int t2 = 0; t2 < 2; ++t2) { aoff[t2] = (unsigned)((t2 * 16 + fr) * lda + fq * 8) * 2u; boff[t2] = (unsigned)((t2 * 16 + fr) * ldb + fq * 8) * 2u; }
;         bf16x8_t av[NST][2], bv[NST][2];
; #pragma unroll
;         for (int st = 0; st < NST; ++st)
; #pragma unroll
;             for (int t2 = 0; t2 < 2; ++t2) { av[st][t2] = *(const bf16x8_t*)(abase + st * 64 + aoff[t2]); bv[st][t2] = *(const bf16x8_t*)(bbase + st * 64 + boff[t2]); }
;         f32x4 acc[2][2];
; #pragma unroll
;         for (int mt = 0; mt < 2; ++mt)
; #pragma unroll
;             for (int nt = 0; nt < 2; ++nt) acc[mt][nt] = (f32x4){0.f, 0.f, 0.f, 0.f};
; #pragma unroll
;         for (int st = 0; st < NST; ++st)
; #pragma unroll
;             for (int mt = 0; mt < 2; ++mt)
; #pragma unroll
;                 for (int nt = 0; nt < 2; ++nt) acc[mt][nt] = MFMA16(bv[st][nt], av[st][mt], acc[mt][nt]);
;         __syncthreads();
;         LAS float* tk = tile + w * (32 * SG32_LD);
; #pragma unroll
;         for (int mt = 0; mt < 2; ++mt)
; #pragma unroll
;             for (int nt = 0; nt < 2; ++nt) *(LAS f32x4*)(tk + (mt * 16 + fr) * SG32_LD + nt * 16 + fq * 4) = acc[mt][nt];
;         __syncthreads();
;         if (tid < 128) {
;             const int r = tid >> 2, cq = (tid & 3) * 8;
;             f32x4 x0 = *(const LAS f32x4*)(tile + r * SG32_LD + cq), x1 = *(const LAS f32x4*)(tile + r * SG32_LD + cq + 4);
; #pragma unroll
;             for (int q = 1; q < 8; ++q) { x0 += *(const LAS f32x4*)(tile + q * (32 * SG32_LD) + r * SG32_LD + cq); x1 += *(const LAS f32x4*)(tile + q * (32 * SG32_LD) + r * SG32_LD + cq + 4); }
;             const float v[8] = {x0[0], x0[1], x0[2], x0[3], x1[0], x1[1], x1[2], x1[3]};
;             const int row = MP + rb * 32 + r;
;             if constexpr (MODE == 0) f.apply8(row, cb * 32 + cq, v, f.rowctx(row));
.LBB0_1248:
	s_and_b32 s16, s20, 0xffffffe0
	s_and_b32 s24, s22, 0x60
	s_ashr_i32 s17, s16, 31
	s_lshl_b64 s[10:11], s[16:17], 11
	s_lshl_b32 s17, s24, 12
	s_add_u32 s26, s6, s17
	s_addc_u32 s27, s7, 0
	s_add_u32 s10, s18, s10
	s_addc_u32 s11, s19, s11
	v_lshl_add_u64 v[12:13], s[10:11], 0, v[6:7]
	v_lshl_add_u64 v[42:43], s[26:27], 0, v[172:173]
	v_lshl_add_u64 v[44:45], s[10:11], 0, v[10:11]
	v_lshl_add_u64 v[46:47], s[26:27], 0, v[8:9]
	global_load_dwordx4 v[48:51], v[12:13], off
	global_load_dwordx4 v[52:55], v[42:43], off
	global_load_dwordx4 v[56:59], v[44:45], off
	global_load_dwordx4 v[60:63], v[46:47], off
	global_load_dwordx4 v[64:67], v[12:13], off offset:64
	global_load_dwordx4 v[68:71], v[42:43], off offset:64
	global_load_dwordx4 v[72:75], v[44:45], off offset:64
	global_load_dwordx4 v[76:79], v[46:47], off offset:64
	global_load_dwordx4 v[80:83], v[12:13], off offset:128
	global_load_dwordx4 v[84:87], v[42:43], off offset:128
	global_load_dwordx4 v[88:91], v[44:45], off offset:128
	global_load_dwordx4 v[92:95], v[46:47], off offset:128
	global_load_dwordx4 v[96:99], v[12:13], off offset:192
	global_load_dwordx4 v[100:103], v[42:43], off offset:192
	global_load_dwordx4 v[104:107], v[44:45], off offset:192
	global_load_dwordx4 v[108:111], v[46:47], off offset:192
	s_waitcnt vmcnt(12)
	v_mfma_f32_16x16x32_bf16 v[22:25], v[48:51], v[52:55], 0
	v_mfma_f32_16x16x32_bf16 v[18:21], v[56:59], v[52:55], 0
	v_mfma_f32_16x16x32_bf16 v[2:5], v[48:51], v[60:63], 0
	v_mfma_f32_16x16x32_bf16 v[26:29], v[56:59], v[60:63], 0
	s_waitcnt vmcnt(8)
	v_mfma_f32_16x16x32_bf16 v[22:25], v[64:67], v[68:71], v[22:25]
	v_mfma_f32_16x16x32_bf16 v[18:21], v[72:75], v[68:71], v[18:21]
	v_mfma_f32_16x16x32_bf16 v[2:5], v[64:67], v[76:79], v[2:5]
	v_mfma_f32_16x16x32_bf16 v[26:29], v[72:75], v[76:79], v[26:29]
	s_waitcnt vmcnt(4)
	v_mfma_f32_16x16x32_bf16 v[22:25], v[80:83], v[84:87], v[22:25]
	v_mfma_f32_16x16x32_bf16 v[18:21], v[88:91], v[84:87], v[18:21]
	v_mfma_f32_16x16x32_bf16 v[2:5], v[80:83], v[92:95], v[2:5]
	v_mfma_f32_16x16x32_bf16 v[26:29], v[88:91], v[92:95], v[26:29]
	s_waitcnt vmcnt(0)
	v_mfma_f32_16x16x32_bf16 v[22:25], v[96:99], v[100:103], v[22:25]
	v_mfma_f32_16x16x32_bf16 v[18:21], v[104:107], v[100:103], v[18:21]
	v_mfma_f32_16x16x32_bf16 v[2:5], v[96:99], v[108:111], v[2:5]
	v_mfma_f32_16x16x32_bf16 v[26:29], v[104:107], v[108:111], v[26:29]
	s_barrier
	s_nop 7
	s_nop 1
	ds_write_b128 v17, v[22:25]
	ds_write_b128 v17, v[18:21] offset:64
	ds_write_b128 v17, v[2:5] offset:2304
	ds_write_b128 v17, v[26:29] offset:2368
	s_waitcnt lgkmcnt(0)
	s_barrier
	s_and_saveexec_b64 s[10:11], vcc
	s_cbranch_execz .LBB0_1247
	ds_read_b128 v[2:5], v15
	ds_read_b128 v[18:21], v15 offset:16
	ds_read_b128 v[22:25], v15 offset:4608
	s_waitcnt lgkmcnt(0)
	v_pk_add_f32 v[12:13], v[4:5], v[24:25]
	v_pk_add_f32 v[22:23], v[2:3], v[22:23]
	ds_read_b128 v[2:5], v15 offset:4624
	s_waitcnt lgkmcnt(0)
	v_pk_add_f32 v[20:21], v[20:21], v[4:5]
	v_pk_add_f32 v[18:19], v[18:19], v[2:3]
	ds_read_b128 v[2:5], v15 offset:9216
	s_waitcnt lgkmcnt(0)
	v_pk_add_f32 v[12:13], v[12:13], v[4:5]
	v_pk_add_f32 v[22:23], v[22:23], v[2:3]
	ds_read_b128 v[2:5], v15 offset:9232
	s_waitcnt lgkmcnt(0)
	v_pk_add_f32 v[20:21], v[20:21], v[4:5]
	v_pk_add_f32 v[18:19], v[18:19], v[2:3]
	ds_read_b128 v[2:5], v15 offset:13824
	s_waitcnt lgkmcnt(0)
	v_pk_add_f32 v[12:13], v[12:13], v[4:5]
	v_pk_add_f32 v[22:23], v[22:23], v[2:3]
	ds_read_b128 v[2:5], v15 offset:13840
	s_waitcnt lgkmcnt(0)
	v_pk_add_f32 v[20:21], v[20:21], v[4:5]
	v_pk_add_f32 v[18:19], v[18:19], v[2:3]
	ds_read_b128 v[2:5], v15 offset:18432
	s_waitcnt lgkmcnt(0)
	v_pk_add_f32 v[12:13], v[12:13], v[4:5]
	v_pk_add_f32 v[22:23], v[22:23], v[2:3]
	ds_read_b128 v[2:5], v15 offset:18448
	s_waitcnt lgkmcnt(0)
	v_pk_add_f32 v[20:21], v[20:21], v[4:5]
	v_pk_add_f32 v[18:19], v[18:19], v[2:3]
	ds_read_b128 v[2:5], v15 offset:23040
	s_waitcnt lgkmcnt(0)
	v_pk_add_f32 v[12:13], v[12:13], v[4:5]
	v_pk_add_f32 v[22:23], v[22:23], v[2:3]
	ds_read_b128 v[2:5], v15 offset:23056
	s_waitcnt lgkmcnt(0)
	v_pk_add_f32 v[20:21], v[20:21], v[4:5]
	v_pk_add_f32 v[18:19], v[18:19], v[2:3]
	ds_read_b128 v[2:5], v15 offset:27648
	s_waitcnt lgkmcnt(0)
	v_pk_add_f32 v[12:13], v[12:13], v[4:5]
	v_pk_add_f32 v[22:23], v[22:23], v[2:3]
	ds_read_b128 v[2:5], v15 offset:27664
	s_waitcnt lgkmcnt(0)
	v_pk_add_f32 v[20:21], v[20:21], v[4:5]
	v_pk_add_f32 v[18:19], v[18:19], v[2:3]
	ds_read_b128 v[2:5], v15 offset:32256
	s_waitcnt lgkmcnt(0)
	v_pk_add_f32 v[24:25], v[12:13], v[4:5]
	v_pk_add_f32 v[22:23], v[22:23], v[2:3]
	ds_read_b128 v[2:5], v15 offset:32272
	s_waitcnt lgkmcnt(0)
	v_pk_add_f32 v[28:29], v[18:19], v[2:3]
	v_add_u32_e32 v2, s24, v16
	v_pk_add_f32 v[26:27], v[20:21], v[4:5]
	v_or_b32_e32 v4, s16, v14
	v_ashrrev_i32_e32 v3, 31, v2
	v_lshlrev_b64 v[30:31], 12, v[2:3]
	v_ashrrev_i32_e32 v5, 31, v4
	v_lshl_add_u64 v[2:3], s[12:13], 0, v[30:31]
	v_lshlrev_b64 v[12:13], 1, v[4:5]
	v_lshl_add_u64 v[18:19], s[8:9], 0, v[30:31]
	v_lshl_add_u64 v[2:3], v[2:3], 0, v[12:13]
	v_lshl_add_u64 v[18:19], v[18:19], 0, v[12:13]
	global_load_dwordx4 v[2:5], v[2:3], off
	s_nop 0
	global_load_dwordx4 v[18:21], v[18:19], off
	s_waitcnt vmcnt(1)
	v_lshlrev_b32_e32 v32, 16, v2
	v_and_b32_e32 v33, 0xffff0000, v2
	s_waitcnt vmcnt(0)
	v_lshlrev_b32_e32 v34, 16, v18
	v_and_b32_e32 v35, 0xffff0000, v18
	v_lshlrev_b32_e32 v2, 16, v3
	v_and_b32_e32 v3, 0xffff0000, v3
	v_lshlrev_b32_e32 v18, 16, v19
	v_and_b32_e32 v19, 0xffff0000, v19
	v_pk_fma_f32 v[18:19], v[24:25], v[2:3], v[18:19]
	v_lshlrev_b32_e32 v2, 16, v4
	v_and_b32_e32 v3, 0xffff0000, v4
	v_lshlrev_b32_e32 v24, 16, v20
	v_and_b32_e32 v25, 0xffff0000, v20
	v_pk_fma_f32 v[24:25], v[28:29], v[2:3], v[24:25]
	v_lshlrev_b32_e32 v2, 16, v5
	v_and_b32_e32 v3, 0xffff0000, v5
	v_lshlrev_b32_e32 v4, 16, v21
	v_and_b32_e32 v5, 0xffff0000, v21
	v_pk_fma_f32 v[22:23], v[22:23], v[32:33], v[34:35]
	v_pk_fma_f32 v[20:21], v[26:27], v[2:3], v[4:5]
	v_cvt_pk_bf16_f32 v3, v18, v19
	v_lshl_add_u64 v[18:19], s[14:15], 0, v[30:31]
	v_cvt_pk_bf16_f32 v2, v22, v23
	v_cvt_pk_bf16_f32 v4, v24, v25
	v_cvt_pk_bf16_f32 v5, v20, v21
	v_lshl_add_u64 v[12:13], v[18:19], 0, v[12:13]
	global_store_dwordx4 v[12:13], v[2:5], off
	s_branch .LBB0_1247

; #define MFMA16(a, b, c) __builtin_amdgcn_mfma_f32_16x16x32_bf16((a), (b), (c), 0, 0, 0)
; template <int MODE, int NST, class F>
; __device__ __forceinline__ void sample_gemm32(const bf16_t* A, int lda, const bf16_t* Bt, int ldb, int N, const F& f, float* aux, LAS unsigned char* lds, int wg, int nwg) {
;     ...
;     for (int item = wg; item < nitems; item += nwg) {
;         const int rb = item & 3, cb = item >> 2;
;         const char* abase = (const char*)(A + (size_t)(rb * 32) * lda + w * Kw);
;         const char* bbase = (const char*)(Bt + (size_t)(cb * 32) * ldb + w * Kw);
;         unsigned aoff[2], boff[2];
; #pragma unroll
;         for (int t2 = 0; t2 < 2; ++t2) { aoff[t2] = (unsigned)((t2 * 16 + fr) * lda + fq * 8) * 2u; boff[t2] = (unsigned)((t2 * 16 + fr) * ldb + fq * 8) * 2u; }
;         bf16x8_t av[NST][2], bv[NST][2];
; #pragma unroll
;         for (int st = 0; st < NST; ++st)
; #pragma unroll
;             for (int t2 = 0; t2 < 2; ++t2) { av[st][t2] = *(const bf16x8_t*)(abase + st * 64 + aoff[t2]); bv[st][t2] = *(const bf16x8_t*)(bbase + st * 64 + boff[t2]); }
;         f32x4 acc[2][2];
; #pragma unroll
;         for (int mt = 0; mt < 2; ++mt)
; #pragma unroll
;             for (int nt = 0; nt < 2; ++nt) acc[mt][nt] = (f32x4){0.f, 0.f, 0.f, 0.f};
; #pragma unroll
;         for (int st = 0; st < NST; ++st)
; #pragma unroll
;             for (int mt = 0; mt < 2; ++mt)
; #pragma unroll
;                 for (int nt = 0; nt < 2; ++nt) acc[mt][nt] = MFMA16(bv[st][nt], av[st][mt], acc[mt][nt]);
.LBB0_1389:
	s_and_b32 s10, s16, 0xffffffe0
	s_and_b32 s20, s18, 0x60
	s_ashr_i32 s11, s10, 31
	s_lshl_b64 s[12:13], s[10:11], 12
	s_lshl_b32 s11, s20, 12
	s_add_u32 s22, s6, s11
	s_addc_u32 s23, s7, 0
	s_add_u32 s12, s14, s12
	s_addc_u32 s13, s15, s13
	v_lshl_add_u64 v[42:43], s[12:13], 0, v[172:173]
	v_lshl_add_u64 v[44:45], s[22:23], 0, v[172:173]
	v_lshl_add_u64 v[46:47], s[12:13], 0, v[2:3]
	v_lshl_add_u64 v[4:5], s[22:23], 0, v[2:3]
	global_load_dwordx4 v[48:51], v[42:43], off
	global_load_dwordx4 v[52:55], v[44:45], off
	global_load_dwordx4 v[56:59], v[46:47], off
	global_load_dwordx4 v[60:63], v[4:5], off
	global_load_dwordx4 v[64:67], v[42:43], off offset:64
	global_load_dwordx4 v[68:71], v[44:45], off offset:64
	global_load_dwordx4 v[72:75], v[46:47], off offset:64
	global_load_dwordx4 v[76:79], v[4:5], off offset:64
	global_load_dwordx4 v[80:83], v[42:43], off offset:128
	global_load_dwordx4 v[84:87], v[44:45], off offset:128
	global_load_dwordx4 v[88:91], v[46:47], off offset:128
	global_load_dwordx4 v[92:95], v[4:5], off offset:128
	global_load_dwordx4 v[96:99], v[42:43], off offset:192
	global_load_dwordx4 v[100:103], v[44:45], off offset:192
	global_load_dwordx4 v[104:107], v[46:47], off offset:192
	global_load_dwordx4 v[108:111], v[4:5], off offset:192
	global_load_dwordx4 v[112:115], v[42:43], off offset:256
	global_load_dwordx4 v[116:119], v[44:45], off offset:256
	global_load_dwordx4 v[120:123], v[46:47], off offset:256
	global_load_dwordx4 v[124:127], v[4:5], off offset:256
	global_load_dwordx4 v[132:135], v[42:43], off offset:320
	global_load_dwordx4 v[152:155], v[44:45], off offset:320
	global_load_dwordx4 v[156:159], v[46:47], off offset:320
	global_load_dwordx4 v[160:163], v[4:5], off offset:320
	global_load_dwordx4 v[164:167], v[42:43], off offset:384
	global_load_dwordx4 v[196:199], v[44:45], off offset:384
	global_load_dwordx4 v[200:203], v[46:47], off offset:384
	global_load_dwordx4 v[204:207], v[4:5], off offset:384
	global_load_dwordx4 v[220:223], v[42:43], off offset:448
	global_load_dwordx4 v[224:227], v[44:45], off offset:448
	global_load_dwordx4 v[228:231], v[46:47], off offset:448
	global_load_dwordx4 v[232:235], v[4:5], off offset:448
	s_waitcnt vmcnt(28)
	v_mfma_f32_16x16x32_bf16 v[22:25], v[48:51], v[52:55], 0
	v_mfma_f32_16x16x32_bf16 v[14:17], v[56:59], v[52:55], 0
	v_mfma_f32_16x16x32_bf16 v[10:13], v[48:51], v[60:63], 0
	v_mfma_f32_16x16x32_bf16 v[18:21], v[56:59], v[60:63], 0
	s_waitcnt vmcnt(24)
	v_mfma_f32_16x16x32_bf16 v[22:25], v[64:67], v[68:71], v[22:25]
	v_mfma_f32_16x16x32_bf16 v[14:17], v[72:75], v[68:71], v[14:17]
	v_mfma_f32_16x16x32_bf16 v[10:13], v[64:67], v[76:79], v[10:13]
	v_mfma_f32_16x16x32_bf16 v[18:21], v[72:75], v[76:79], v[18:21]
	s_waitcnt vmcnt(20)
	v_mfma_f32_16x16x32_bf16 v[22:25], v[80:83], v[84:87], v[22:25]
	v_mfma_f32_16x16x32_bf16 v[14:17], v[88:91], v[84:87], v[14:17]
	v_mfma_f32_16x16x32_bf16 v[10:13], v[80:83], v[92:95], v[10:13]
	v_mfma_f32_16x16x32_bf16 v[18:21], v[88:91], v[92:95], v[18:21]
	s_waitcnt vmcnt(16)
	v_mfma_f32_16x16x32_bf16 v[22:25], v[96:99], v[100:103], v[22:25]
	v_mfma_f32_16x16x32_bf16 v[14:17], v[104:107], v[100:103], v[14:17]
	v_mfma_f32_16x16x32_bf16 v[10:13], v[96:99], v[108:111], v[10:13]
	v_mfma_f32_16x16x32_bf16 v[18:21], v[104:107], v[108:111], v[18:21]
	s_waitcnt vmcnt(12)
	v_mfma_f32_16x16x32_bf16 v[22:25], v[112:115], v[116:119], v[22:25]
	v_mfma_f32_16x16x32_bf16 v[14:17], v[120:123], v[116:119], v[14:17]
	v_mfma_f32_16x16x32_bf16 v[10:13], v[112:115], v[124:127], v[10:13]
	v_mfma_f32_16x16x32_bf16 v[18:21], v[120:123], v[124:127], v[18:21]
	s_waitcnt vmcnt(8)
	v_mfma_f32_16x16x32_bf16 v[22:25], v[132:135], v[152:155], v[22:25]
	v_mfma_f32_16x16x32_bf16 v[14:17], v[156:159], v[152:155], v[14:17]
	v_mfma_f32_16x16x32_bf16 v[10:13], v[132:135], v[160:163], v[10:13]
	v_mfma_f32_16x16x32_bf16 v[18:21], v[156:159], v[160:163], v[18:21]
	s_waitcnt vmcnt(4)
	v_mfma_f32_16x16x32_bf16 v[22:25], v[164:167], v[196:199], v[22:25]
	v_mfma_f32_16x16x32_bf16 v[14:17], v[200:203], v[196:199], v[14:17]
	v_mfma_f32_16x16x32_bf16 v[10:13], v[164:167], v[204:207], v[10:13]
	v_mfma_f32_16x16x32_bf16 v[18:21], v[200:203], v[204:207], v[18:21]
	s_waitcnt vmcnt(0)
	v_mfma_f32_16x16x32_bf16 v[22:25], v[220:223], v[224:227], v[22:25]
	v_mfma_f32_16x16x32_bf16 v[14:17], v[228:231], v[224:227], v[14:17]
	v_mfma_f32_16x16x32_bf16 v[10:13], v[220:223], v[232:235], v[10:13]
	v_mfma_f32_16x16x32_bf16 v[18:21], v[228:231], v[232:235], v[18:21]
	s_barrier
; #define LAS __attribute__((address_space(3)))
; template <int MODE, int NST, class F>
; __device__ __forceinline__ void sample_gemm32(const bf16_t* A, int lda, const bf16_t* Bt, int ldb, int N, const F& f, float* aux, LAS unsigned char* lds, int wg, int nwg) {
;     ...
;         __syncthreads();
;         LAS float* tk = tile + w * (32 * SG32_LD);
; #pragma unroll
;         for (int mt = 0; mt < 2; ++mt)
; #pragma unroll
;             for (int nt = 0; nt < 2; ++nt) *(LAS f32x4*)(tk + (mt * 16 + fr) * SG32_LD + nt * 16 + fq * 4) = acc[mt][nt];
;         __syncthreads();
;         if (tid < 128) {
;             const int r = tid >> 2, cq = (tid & 3) * 8;
;             f32x4 x0 = *(const LAS f32x4*)(tile + r * SG32_LD + cq), x1 = *(const LAS f32x4*)(tile + r * SG32_LD + cq + 4);
; #pragma unroll
;             for (int q = 1; q < 8; ++q) { x0 += *(const LAS f32x4*)(tile + q * (32 * SG32_LD) + r * SG32_LD + cq); x1 += *(const LAS f32x4*)(tile + q * (32 * SG32_LD) + r * SG32_LD + cq + 4); }
;             const float v[8] = {x0[0], x0[1], x0[2], x0[3], x1[0], x1[1], x1[2], x1[3]};
;             const int row = MP + rb * 32 + r;
;             if constexpr (MODE == 0) f.apply8(row, cb * 32 + cq, v, f.rowctx(row));
;             else { float ssum = f.apply8s(row, cb * 32 + cq, v); ssum += __shfl_xor(ssum, 1); ssum += __shfl_xor(ssum, 2); if ((tid & 3) == 0) aux[(size_t)row * SSQW + cb] = ssum; }
;         }
	s_nop 7
	s_nop 1
	ds_write_b128 v9, v[22:25]
	ds_write_b128 v9, v[14:17] offset:64
	ds_write_b128 v9, v[10:13] offset:2304
	ds_write_b128 v9, v[18:21] offset:2368
	s_waitcnt lgkmcnt(0)
	s_barrier
	s_and_saveexec_b64 s[12:13], vcc
	s_cbranch_execz .LBB0_1388
	ds_read_b128 v[10:13], v8
	ds_read_b128 v[14:17], v8 offset:16
	ds_read_b128 v[18:21], v8 offset:4608
	s_waitcnt lgkmcnt(0)
	v_pk_add_f32 v[4:5], v[12:13], v[20:21]
	v_pk_add_f32 v[18:19], v[10:11], v[18:19]
	ds_read_b128 v[10:13], v8 offset:4624
	s_waitcnt lgkmcnt(0)
	v_pk_add_f32 v[16:17], v[16:17], v[12:13]
	v_pk_add_f32 v[14:15], v[14:15], v[10:11]
	ds_read_b128 v[10:13], v8 offset:9216
	s_waitcnt lgkmcnt(0)
	v_pk_add_f32 v[4:5], v[4:5], v[12:13]
	v_pk_add_f32 v[18:19], v[18:19], v[10:11]
	ds_read_b128 v[10:13], v8 offset:9232
	s_waitcnt lgkmcnt(0)
	v_pk_add_f32 v[16:17], v[16:17], v[12:13]
	v_pk_add_f32 v[14:15], v[14:15], v[10:11]
	ds_read_b128 v[10:13], v8 offset:13824
	s_waitcnt lgkmcnt(0)
	v_pk_add_f32 v[4:5], v[4:5], v[12:13]
	v_pk_add_f32 v[18:19], v[18:19], v[10:11]
	ds_read_b128 v[10:13], v8 offset:13840
	s_waitcnt lgkmcnt(0)
	v_pk_add_f32 v[16:17], v[16:17], v[12:13]
	v_pk_add_f32 v[14:15], v[14:15], v[10:11]
	ds_read_b128 v[10:13], v8 offset:18432
	s_waitcnt lgkmcnt(0)
	v_pk_add_f32 v[4:5], v[4:5], v[12:13]
	v_pk_add_f32 v[18:19], v[18:19], v[10:11]
	ds_read_b128 v[10:13], v8 offset:18448
	s_waitcnt lgkmcnt(0)
	v_pk_add_f32 v[16:17], v[16:17], v[12:13]
	v_pk_add_f32 v[14:15], v[14:15], v[10:11]
	ds_read_b128 v[10:13], v8 offset:23040
	s_waitcnt lgkmcnt(0)
	v_pk_add_f32 v[4:5], v[4:5], v[12:13]
	v_pk_add_f32 v[18:19], v[18:19], v[10:11]
	ds_read_b128 v[10:13], v8 offset:23056
	s_waitcnt lgkmcnt(0)
	v_pk_add_f32 v[16:17], v[16:17], v[12:13]
	v_pk_add_f32 v[14:15], v[14:15], v[10:11]
	ds_read_b128 v[10:13], v8 offset:27648
	s_waitcnt lgkmcnt(0)
	v_pk_add_f32 v[4:5], v[4:5], v[12:13]
	v_pk_add_f32 v[18:19], v[18:19], v[10:11]
	ds_read_b128 v[10:13], v8 offset:27664
	s_waitcnt lgkmcnt(0)
	v_pk_add_f32 v[20:21], v[16:17], v[12:13]
	v_pk_add_f32 v[22:23], v[14:15], v[10:11]
	ds_read_b128 v[10:13], v8 offset:32256
	ds_read_b128 v[14:17], v8 offset:32272
	s_waitcnt lgkmcnt(1)
	v_pk_add_f32 v[10:11], v[18:19], v[10:11]
	v_add_u32_e32 v18, s20, v6
	v_ashrrev_i32_e32 v19, 31, v18
	v_pk_add_f32 v[12:13], v[4:5], v[12:13]
	v_or_b32_e32 v4, s10, v7
	v_lshlrev_b64 v[18:19], 13, v[18:19]
	v_lshl_add_u64 v[18:19], s[0:1], 0, v[18:19]
	v_ashrrev_i32_e32 v5, 31, v4
	v_lshl_add_u64 v[4:5], v[4:5], 2, v[18:19]
	s_waitcnt lgkmcnt(0)
	v_pk_add_f32 v[16:17], v[20:21], v[16:17]
	v_pk_add_f32 v[14:15], v[22:23], v[14:15]
	global_store_dwordx4 v[4:5], v[10:13], off
	global_store_dwordx4 v[4:5], v[14:17], off offset:16
	s_branch .LBB0_1388

; #define MFMA16(a, b, c) __builtin_amdgcn_mfma_f32_16x16x32_bf16((a), (b), (c), 0, 0, 0)
; template <int MODE, int NST, class F>
; __device__ __forceinline__ void sample_gemm32(const bf16_t* A, int lda, const bf16_t* Bt, int ldb, int N, const F& f, float* aux, LAS unsigned char* lds, int wg, int nwg) {
;     ...
;     for (int item = wg; item < nitems; item += nwg) {
;         const int rb = item & 3, cb = item >> 2;
;         const char* abase = (const char*)(A + (size_t)(rb * 32) * lda + w * Kw);
;         const char* bbase = (const char*)(Bt + (size_t)(cb * 32) * ldb + w * Kw);
;         unsigned aoff[2], boff[2];
; #pragma unroll
;         for (int t2 = 0; t2 < 2; ++t2) { aoff[t2] = (unsigned)((t2 * 16 + fr) * lda + fq * 8) * 2u; boff[t2] = (unsigned)((t2 * 16 + fr) * ldb + fq * 8) * 2u; }
;         bf16x8_t av[NST][2], bv[NST][2];
; #pragma unroll
;         for (int st = 0; st < NST; ++st)
; #pragma unroll
;             for (int t2 = 0; t2 < 2; ++t2) { av[st][t2] = *(const bf16x8_t*)(abase + st * 64 + aoff[t2]); bv[st][t2] = *(const bf16x8_t*)(bbase + st * 64 + boff[t2]); }
;         f32x4 acc[2][2];
; #pragma unroll
;         for (int mt = 0; mt < 2; ++mt)
; #pragma unroll
;             for (int nt = 0; nt < 2; ++nt) acc[mt][nt] = (f32x4){0.f, 0.f, 0.f, 0.f};
; #pragma unroll
;         for (int st = 0; st < NST; ++st)
; #pragma unroll
;             for (int mt = 0; mt < 2; ++mt)
; #pragma unroll
;                 for (int nt = 0; nt < 2; ++nt) acc[mt][nt] = MFMA16(bv[st][nt], av[st][mt], acc[mt][nt]);
.LBB0_2023:
	s_ashr_i32 s20, s92, 2
	s_lshl_b32 s24, s20, 5
	s_and_b32 s21, s28, 0x60
	s_ashr_i32 s25, s24, 31
	s_lshl_b64 s[22:23], s[24:25], 12
	s_lshl_b32 s25, s21, 12
	s_add_u32 s30, s6, s25
	s_addc_u32 s31, s7, 0
	s_add_u32 s22, s26, s22
	s_addc_u32 s23, s27, s23
	v_lshl_add_u64 v[12:13], s[22:23], 0, v[172:173]
	v_lshl_add_u64 v[24:25], s[30:31], 0, v[172:173]
	v_lshl_add_u64 v[46:47], s[22:23], 0, v[14:15]
	s_waitcnt lgkmcnt(0)
	v_lshl_add_u64 v[2:3], s[30:31], 0, v[14:15]
	global_load_dwordx4 v[48:51], v[12:13], off
	global_load_dwordx4 v[52:55], v[24:25], off
	global_load_dwordx4 v[56:59], v[46:47], off
	global_load_dwordx4 v[60:63], v[2:3], off
	global_load_dwordx4 v[64:67], v[12:13], off offset:64
	global_load_dwordx4 v[68:71], v[24:25], off offset:64
	global_load_dwordx4 v[72:75], v[46:47], off offset:64
	global_load_dwordx4 v[76:79], v[2:3], off offset:64
	global_load_dwordx4 v[80:83], v[12:13], off offset:128
	global_load_dwordx4 v[84:87], v[24:25], off offset:128
	global_load_dwordx4 v[88:91], v[46:47], off offset:128
	global_load_dwordx4 v[92:95], v[2:3], off offset:128
	global_load_dwordx4 v[96:99], v[12:13], off offset:192
	global_load_dwordx4 v[100:103], v[24:25], off offset:192
	global_load_dwordx4 v[104:107], v[46:47], off offset:192
	global_load_dwordx4 v[108:111], v[2:3], off offset:192
	global_load_dwordx4 v[112:115], v[12:13], off offset:256
	global_load_dwordx4 v[116:119], v[24:25], off offset:256
	global_load_dwordx4 v[120:123], v[46:47], off offset:256
	global_load_dwordx4 v[124:127], v[2:3], off offset:256
	global_load_dwordx4 v[132:135], v[12:13], off offset:320
	global_load_dwordx4 v[152:155], v[24:25], off offset:320
	global_load_dwordx4 v[156:159], v[46:47], off offset:320
	global_load_dwordx4 v[160:163], v[2:3], off offset:320
	global_load_dwordx4 v[164:167], v[12:13], off offset:384
	global_load_dwordx4 v[196:199], v[24:25], off offset:384
	global_load_dwordx4 v[200:203], v[46:47], off offset:384
	global_load_dwordx4 v[204:207], v[2:3], off offset:384
	global_load_dwordx4 v[220:223], v[12:13], off offset:448
	global_load_dwordx4 v[224:227], v[24:25], off offset:448
	global_load_dwordx4 v[228:231], v[46:47], off offset:448
	global_load_dwordx4 v[232:235], v[2:3], off offset:448
	s_waitcnt vmcnt(28)
	v_mfma_f32_16x16x32_bf16 v[20:23], v[48:51], v[52:55], 0
	v_mfma_f32_16x16x32_bf16 v[8:11], v[56:59], v[52:55], 0
	v_mfma_f32_16x16x32_bf16 v[4:7], v[48:51], v[60:63], 0
	v_mfma_f32_16x16x32_bf16 v[16:19], v[56:59], v[60:63], 0
	s_waitcnt vmcnt(24)
	v_mfma_f32_16x16x32_bf16 v[20:23], v[64:67], v[68:71], v[20:23]
	v_mfma_f32_16x16x32_bf16 v[8:11], v[72:75], v[68:71], v[8:11]
	v_mfma_f32_16x16x32_bf16 v[4:7], v[64:67], v[76:79], v[4:7]
	v_mfma_f32_16x16x32_bf16 v[16:19], v[72:75], v[76:79], v[16:19]
	s_waitcnt vmcnt(20)
	v_mfma_f32_16x16x32_bf16 v[20:23], v[80:83], v[84:87], v[20:23]
	v_mfma_f32_16x16x32_bf16 v[8:11], v[88:91], v[84:87], v[8:11]
	v_mfma_f32_16x16x32_bf16 v[4:7], v[80:83], v[92:95], v[4:7]
	v_mfma_f32_16x16x32_bf16 v[16:19], v[88:91], v[92:95], v[16:19]
	s_waitcnt vmcnt(16)
	v_mfma_f32_16x16x32_bf16 v[20:23], v[96:99], v[100:103], v[20:23]
	v_mfma_f32_16x16x32_bf16 v[8:11], v[104:107], v[100:103], v[8:11]
	v_mfma_f32_16x16x32_bf16 v[4:7], v[96:99], v[108:111], v[4:7]
	v_mfma_f32_16x16x32_bf16 v[16:19], v[104:107], v[108:111], v[16:19]
	s_waitcnt vmcnt(12)
	v_mfma_f32_16x16x32_bf16 v[20:23], v[112:115], v[116:119], v[20:23]
	v_mfma_f32_16x16x32_bf16 v[8:11], v[120:123], v[116:119], v[8:11]
	v_mfma_f32_16x16x32_bf16 v[4:7], v[112:115], v[124:127], v[4:7]
	v_mfma_f32_16x16x32_bf16 v[16:19], v[120:123], v[124:127], v[16:19]
	s_waitcnt vmcnt(8)
	v_mfma_f32_16x16x32_bf16 v[20:23], v[132:135], v[152:155], v[20:23]
	v_mfma_f32_16x16x32_bf16 v[8:11], v[156:159], v[152:155], v[8:11]
	v_mfma_f32_16x16x32_bf16 v[4:7], v[132:135], v[160:163], v[4:7]
	v_mfma_f32_16x16x32_bf16 v[16:19], v[156:159], v[160:163], v[16:19]
	s_waitcnt vmcnt(4)
	v_mfma_f32_16x16x32_bf16 v[20:23], v[164:167], v[196:199], v[20:23]
	v_mfma_f32_16x16x32_bf16 v[8:11], v[200:203], v[196:199], v[8:11]
	v_mfma_f32_16x16x32_bf16 v[4:7], v[164:167], v[204:207], v[4:7]
	v_mfma_f32_16x16x32_bf16 v[16:19], v[200:203], v[204:207], v[16:19]
	s_waitcnt vmcnt(0)
	v_mfma_f32_16x16x32_bf16 v[20:23], v[220:223], v[224:227], v[20:23]
	v_mfma_f32_16x16x32_bf16 v[8:11], v[228:231], v[224:227], v[8:11]
	v_mfma_f32_16x16x32_bf16 v[4:7], v[220:223], v[232:235], v[4:7]
	v_mfma_f32_16x16x32_bf16 v[16:19], v[228:231], v[232:235], v[16:19]
	s_barrier
; #define LAS __attribute__((address_space(3)))
; __device__ __forceinline__ u32x4 pack8(const float (&v)[8]) { u32x4 w; w.x = pk2(v[0], v[1]); w.y = pk2(v[2], v[3]); w.z = pk2(v[4], v[5]); w.w = pk2(v[6], v[7]); return w; }
; __device__ __forceinline__ float sigm(float x) { return __builtin_amdgcn_rcpf(1.f + __builtin_amdgcn_exp2f(x * -1.4426950408889634f)); }
;     __device__ __forceinline__ float apply8s(int row, int col, const float (&a)[8]) const {
;         float e[8], v[8]; unpack8(*(const u32x4*)(pe + (size_t)row * D + col), e);
;         float hh[8]; unpack8(*(const u32x4*)(h2 + (size_t)row * D + col), hh); float s = 0.f;
; #pragma unroll
;         for (int j = 0; j < 8; ++j) { v[j] = hh[j] + sigm(a[j]) * e[j]; s += v[j] * v[j]; }
;         if (out32) { *(f32x4*)(out32 + (size_t)row * D + col) = (f32x4){v[0], v[1], v[2], v[3]}; *(f32x4*)(out32 + (size_t)row * D + col + 4) = (f32x4){v[4], v[5], v[6], v[7]}; }
;         *(u32x4*)(hbf + (size_t)row * D + col) = pack8(v);
; template <int MODE, int NST, class F>
; __device__ __forceinline__ void sample_gemm32(const bf16_t* A, int lda, const bf16_t* Bt, int ldb, int N, const F& f, float* aux, LAS unsigned char* lds, int wg, int nwg) {
;     ...
;         __syncthreads();
;         LAS float* tk = tile + w * (32 * SG32_LD);
; #pragma unroll
;         for (int mt = 0; mt < 2; ++mt)
; #pragma unroll
;             for (int nt = 0; nt < 2; ++nt) *(LAS f32x4*)(tk + (mt * 16 + fr) * SG32_LD + nt * 16 + fq * 4) = acc[mt][nt];
;         __syncthreads();
;         if (tid < 128) {
;             const int r = tid >> 2, cq = (tid & 3) * 8;
;             f32x4 x0 = *(const LAS f32x4*)(tile + r * SG32_LD + cq), x1 = *(const LAS f32x4*)(tile + r * SG32_LD + cq + 4);
; #pragma unroll
;             for (int q = 1; q < 8; ++q) { x0 += *(const LAS f32x4*)(tile + q * (32 * SG32_LD) + r * SG32_LD + cq); x1 += *(const LAS f32x4*)(tile + q * (32 * SG32_LD) + r * SG32_LD + cq + 4); }
;             const float v[8] = {x0[0], x0[1], x0[2], x0[3], x1[0], x1[1], x1[2], x1[3]};
;             const int row = MP + rb * 32 + r;
;             if constexpr (MODE == 0) f.apply8(row, cb * 32 + cq, v, f.rowctx(row));
;             else { float ssum = f.apply8s(row, cb * 32 + cq, v); ssum += __shfl_xor(ssum, 1); ssum += __shfl_xor(ssum, 2); if ((tid & 3) == 0) aux[(size_t)row * SSQW + cb] = ssum; }
	s_nop 7
	s_nop 1
	ds_write_b128 v29, v[20:23]
	ds_write_b128 v29, v[8:11] offset:64
	ds_write_b128 v29, v[4:7] offset:2304
	ds_write_b128 v29, v[16:19] offset:2368
	s_waitcnt lgkmcnt(0)
	s_barrier
	s_and_saveexec_b64 s[22:23], s[36:37]
	s_cbranch_execz .LBB0_2022
	ds_read_b128 v[2:5], v27
	ds_read_b128 v[6:9], v27 offset:16
	ds_read_b128 v[10:13], v27 offset:4608
	v_add_u32_e32 v18, s21, v28
	v_or_b32_e32 v20, s24, v26
	v_ashrrev_i32_e32 v19, 31, v18
	v_ashrrev_i32_e32 v21, 31, v20
	s_waitcnt lgkmcnt(0)
	v_pk_add_f32 v[12:13], v[4:5], v[12:13]
	v_pk_add_f32 v[10:11], v[2:3], v[10:11]
	ds_read_b128 v[2:5], v27 offset:4624
	v_lshlrev_b64 v[30:31], 1, v[20:21]
	v_lshlrev_b64 v[22:23], 11, v[18:19]
	s_andn2_b64 vcc, exec, s[18:19]
	s_waitcnt lgkmcnt(0)
	v_pk_add_f32 v[8:9], v[8:9], v[4:5]
	v_pk_add_f32 v[6:7], v[6:7], v[2:3]
	ds_read_b128 v[2:5], v27 offset:9216
	s_waitcnt lgkmcnt(0)
	v_pk_add_f32 v[12:13], v[12:13], v[4:5]
	v_pk_add_f32 v[10:11], v[10:11], v[2:3]
	ds_read_b128 v[2:5], v27 offset:9232
	s_waitcnt lgkmcnt(0)
	v_pk_add_f32 v[8:9], v[8:9], v[4:5]
	v_pk_add_f32 v[6:7], v[6:7], v[2:3]
	ds_read_b128 v[2:5], v27 offset:13824
	s_waitcnt lgkmcnt(0)
	v_pk_add_f32 v[12:13], v[12:13], v[4:5]
	v_pk_add_f32 v[10:11], v[10:11], v[2:3]
	ds_read_b128 v[2:5], v27 offset:13840
	s_waitcnt lgkmcnt(0)
	v_pk_add_f32 v[8:9], v[8:9], v[4:5]
	v_pk_add_f32 v[6:7], v[6:7], v[2:3]
	ds_read_b128 v[2:5], v27 offset:18432
	s_waitcnt lgkmcnt(0)
	v_pk_add_f32 v[12:13], v[12:13], v[4:5]
	v_pk_add_f32 v[10:11], v[10:11], v[2:3]
	ds_read_b128 v[2:5], v27 offset:18448
	s_waitcnt lgkmcnt(0)
	v_pk_add_f32 v[8:9], v[8:9], v[4:5]
	v_pk_add_f32 v[6:7], v[6:7], v[2:3]
	ds_read_b128 v[2:5], v27 offset:23040
	s_waitcnt lgkmcnt(0)
	v_pk_add_f32 v[12:13], v[12:13], v[4:5]
	v_pk_add_f32 v[10:11], v[10:11], v[2:3]
	ds_read_b128 v[2:5], v27 offset:23056
	s_waitcnt lgkmcnt(0)
	v_pk_add_f32 v[8:9], v[8:9], v[4:5]
	v_pk_add_f32 v[6:7], v[6:7], v[2:3]
	ds_read_b128 v[2:5], v27 offset:27648
	s_waitcnt lgkmcnt(0)
	v_pk_add_f32 v[12:13], v[12:13], v[4:5]
	v_pk_add_f32 v[10:11], v[10:11], v[2:3]
	ds_read_b128 v[2:5], v27 offset:27664
	s_waitcnt lgkmcnt(0)
	v_pk_add_f32 v[8:9], v[8:9], v[4:5]
	v_pk_add_f32 v[6:7], v[6:7], v[2:3]
	ds_read_b128 v[2:5], v27 offset:32256
	s_waitcnt lgkmcnt(0)
	v_pk_add_f32 v[12:13], v[12:13], v[4:5]
	v_pk_add_f32 v[10:11], v[10:11], v[2:3]
	ds_read_b128 v[2:5], v27 offset:32272
	v_mul_f32_e32 v10, 0xbfb8aa3b, v10
	v_mul_f32_e32 v11, 0xbfb8aa3b, v11
	v_exp_f32_e32 v10, v10
	v_exp_f32_e32 v11, v11
	s_waitcnt lgkmcnt(0)
	v_pk_add_f32 v[24:25], v[6:7], v[2:3]
	v_lshlrev_b64 v[2:3], 12, v[18:19]
	v_pk_add_f32 v[16:17], v[8:9], v[4:5]
	v_lshl_add_u64 v[4:5], s[14:15], 0, v[2:3]
	v_lshl_add_u64 v[2:3], s[8:9], 0, v[2:3]
	v_lshl_add_u64 v[4:5], v[4:5], 0, v[30:31]
	v_lshl_add_u64 v[2:3], v[2:3], 0, v[30:31]
	global_load_dwordx4 v[6:9], v[4:5], off
	v_add_f32_e32 v10, 1.0, v10
	global_load_dwordx4 v[2:5], v[2:3], off
	v_add_f32_e32 v11, 1.0, v11
	v_rcp_f32_e32 v10, v10
	v_rcp_f32_e32 v11, v11
	s_waitcnt vmcnt(1)
	v_lshlrev_b32_e32 v30, 16, v6
	v_and_b32_e32 v31, 0xffff0000, v6
	s_waitcnt vmcnt(0)
	v_lshlrev_b32_e32 v32, 16, v2
	v_and_b32_e32 v33, 0xffff0000, v2
	v_mul_f32_e32 v2, 0xbfb8aa3b, v12
	v_exp_f32_e32 v2, v2
	v_lshlrev_b32_e32 v6, 16, v7
	v_and_b32_e32 v7, 0xffff0000, v7
	v_pk_fma_f32 v[10:11], v[10:11], v[30:31], v[32:33]
	v_add_f32_e32 v2, 1.0, v2
	v_rcp_f32_e32 v12, v2
	v_mul_f32_e32 v2, 0xbfb8aa3b, v13
	v_exp_f32_e32 v2, v2
	s_nop 0
	v_add_f32_e32 v2, 1.0, v2
	v_rcp_f32_e32 v13, v2
	v_lshlrev_b32_e32 v2, 16, v3
	v_and_b32_e32 v3, 0xffff0000, v3
	v_pk_fma_f32 v[12:13], v[12:13], v[6:7], v[2:3]
	v_mul_f32_e32 v2, 0xbfb8aa3b, v24
	v_mul_f32_e32 v3, 0xbfb8aa3b, v25
	v_exp_f32_e32 v2, v2
	v_exp_f32_e32 v3, v3
	v_lshlrev_b32_e32 v24, 16, v4
	v_and_b32_e32 v25, 0xffff0000, v4
	v_mul_f32_e32 v4, 0xbfb8aa3b, v16
	v_add_f32_e32 v2, 1.0, v2
	v_add_f32_e32 v3, 1.0, v3
	v_exp_f32_e32 v4, v4
	v_rcp_f32_e32 v2, v2
	v_rcp_f32_e32 v3, v3
	v_lshlrev_b32_e32 v6, 16, v8
	v_and_b32_e32 v7, 0xffff0000, v8
	v_add_f32_e32 v4, 1.0, v4
	v_pk_fma_f32 v[2:3], v[2:3], v[6:7], v[24:25]
	v_rcp_f32_e32 v6, v4
	v_mul_f32_e32 v4, 0xbfb8aa3b, v17
	v_exp_f32_e32 v4, v4
	v_lshlrev_b32_e32 v8, 16, v9
	v_and_b32_e32 v9, 0xffff0000, v9
	v_add_f32_e32 v4, 1.0, v4
	v_rcp_f32_e32 v7, v4
	v_lshlrev_b32_e32 v4, 16, v5
	v_and_b32_e32 v5, 0xffff0000, v5
	v_pk_fma_f32 v[4:5], v[6:7], v[8:9], v[4:5]
	s_cbranch_vccnz .LBB0_2026
	v_lshl_add_u64 v[6:7], v[22:23], 2, s[10:11]
	v_lshl_add_u64 v[6:7], v[20:21], 2, v[6:7]
	global_store_dwordx4 v[6:7], v[10:13], off
	global_store_dwordx4 v[6:7], v[2:5], off offset:16
